# NAT V tiles (transposed V): adjacent rows paired through a quad-perm DPP move so each lane stores one dword instead of two 2-byte stores; contiguous fast path
# baseline (speedup 1.0000x reference)
.Llru_no:
	s_cmp_lg_u32 s79, 19
	s_cbranch_scc1 .Lnatv_no
	s_cmpk_lt_u32 s27, 0x800
	s_cbranch_scc1 .Lnatv_no
	v_and_b32_e32 v246, 0x3ff, v136
	v_lshrrev_b32_e32 v247, 6, v246
	v_and_b32_e32 v246, 63, v246
	v_lshlrev_b32_e32 v247, 20, v247
	v_lshl_or_b32 v246, v246, 14, v247
	v_lshrrev_b32_e32 v247, 13, v138
	v_lshl_or_b32 v246, v247, 24, v246
	v_and_b32_e32 v247, 0x1fff, v138
	v_lshl_or_b32 v246, v247, 1, v246
	v_mbcnt_lo_u32_b32 v247, -1, 0
	v_mbcnt_hi_u32_b32 v247, -1, v247
	v_and_b32_e32 v247, 1, v247
	v_mov_b32_e32 v210, 0x05040100
	v_mov_b32_e32 v211, 0x03020706
	v_cmp_eq_u32_e32 vcc, 1, v247
	s_nop 1
	v_cndmask_b32_e32 v210, v210, v211, vcc
	v_mul_u32_u24_e32 v247, 0x3ffe, v247
	v_add_u32_e32 v246, v246, v247
	v_mov_b32_e32 v247, 0
	v_lshl_add_u64 v[194:195], v[246:247], 0, s[34:35]
	v_add_co_u32_e32 v196, vcc, 0x8000, v194
	v_addc_co_u32_e32 v197, vcc, 0, v195, vcc
	v_add_co_u32_e32 v198, vcc, 0x40000, v194
	v_addc_co_u32_e32 v199, vcc, 0, v195, vcc
	v_add_co_u32_e32 v200, vcc, 0x48000, v194
	v_addc_co_u32_e32 v201, vcc, 0, v195, vcc
	v_add_co_u32_e32 v202, vcc, 0x200000, v194
	v_addc_co_u32_e32 v203, vcc, 0, v195, vcc
	v_add_co_u32_e32 v204, vcc, 0x208000, v194
	v_addc_co_u32_e32 v205, vcc, 0, v195, vcc
	v_add_co_u32_e32 v206, vcc, 0x240000, v194
	v_addc_co_u32_e32 v207, vcc, 0, v195, vcc
	v_add_co_u32_e32 v208, vcc, 0x248000, v194
	v_addc_co_u32_e32 v209, vcc, 0, v195, vcc
	v_cvt_pk_bf16_f32 v212, v124, v125
	v_cvt_pk_bf16_f32 v213, v126, v127
	v_cvt_pk_bf16_f32 v214, v120, v121
	v_cvt_pk_bf16_f32 v215, v122, v123
	s_nop 0
	v_mov_b32_dpp v124, v212 quad_perm:[1,0,3,2] row_mask:0xf bank_mask:0xf
	v_mov_b32_dpp v125, v213 quad_perm:[1,0,3,2] row_mask:0xf bank_mask:0xf
	v_mov_b32_dpp v126, v214 quad_perm:[1,0,3,2] row_mask:0xf bank_mask:0xf
	v_mov_b32_dpp v127, v215 quad_perm:[1,0,3,2] row_mask:0xf bank_mask:0xf
	v_perm_b32 v212, v124, v212, v210
	v_perm_b32 v213, v125, v213, v210
	v_perm_b32 v214, v126, v214, v210
	v_perm_b32 v215, v127, v215, v210
	global_store_dword v[194:195], v212, off
	global_store_dword v[196:197], v213, off
	global_store_dword v[198:199], v214, off
	global_store_dword v[200:201], v215, off
	v_cvt_pk_bf16_f32 v216, v116, v117
	v_cvt_pk_bf16_f32 v217, v118, v119
	v_cvt_pk_bf16_f32 v218, v112, v113
	v_cvt_pk_bf16_f32 v219, v114, v115
	s_nop 0
	v_mov_b32_dpp v116, v216 quad_perm:[1,0,3,2] row_mask:0xf bank_mask:0xf
	v_mov_b32_dpp v117, v217 quad_perm:[1,0,3,2] row_mask:0xf bank_mask:0xf
	v_mov_b32_dpp v118, v218 quad_perm:[1,0,3,2] row_mask:0xf bank_mask:0xf
	v_mov_b32_dpp v119, v219 quad_perm:[1,0,3,2] row_mask:0xf bank_mask:0xf
	v_perm_b32 v216, v116, v216, v210
	v_perm_b32 v217, v117, v217, v210
	v_perm_b32 v218, v118, v218, v210
	v_perm_b32 v219, v119, v219, v210
	global_store_dword v[202:203], v216, off
	global_store_dword v[204:205], v217, off
	global_store_dword v[206:207], v218, off
	global_store_dword v[208:209], v219, off
	v_cvt_pk_bf16_f32 v212, v108, v109
	v_cvt_pk_bf16_f32 v213, v110, v111
	v_cvt_pk_bf16_f32 v214, v104, v105
	v_cvt_pk_bf16_f32 v215, v106, v107
	s_nop 0
	v_mov_b32_dpp v108, v212 quad_perm:[1,0,3,2] row_mask:0xf bank_mask:0xf
	v_mov_b32_dpp v109, v213 quad_perm:[1,0,3,2] row_mask:0xf bank_mask:0xf
	v_mov_b32_dpp v110, v214 quad_perm:[1,0,3,2] row_mask:0xf bank_mask:0xf
	v_mov_b32_dpp v111, v215 quad_perm:[1,0,3,2] row_mask:0xf bank_mask:0xf
	v_perm_b32 v212, v108, v212, v210
	v_perm_b32 v213, v109, v213, v210
	v_perm_b32 v214, v110, v214, v210
	v_perm_b32 v215, v111, v215, v210
	global_store_dword v[194:195], v212, off offset:32
	global_store_dword v[196:197], v213, off offset:32
	global_store_dword v[198:199], v214, off offset:32
	global_store_dword v[200:201], v215, off offset:32
	v_cvt_pk_bf16_f32 v216, v100, v101
	v_cvt_pk_bf16_f32 v217, v102, v103
	v_cvt_pk_bf16_f32 v218, v96, v97
	v_cvt_pk_bf16_f32 v219, v98, v99
	s_nop 0
	v_mov_b32_dpp v100, v216 quad_perm:[1,0,3,2] row_mask:0xf bank_mask:0xf
	v_mov_b32_dpp v101, v217 quad_perm:[1,0,3,2] row_mask:0xf bank_mask:0xf
	v_mov_b32_dpp v102, v218 quad_perm:[1,0,3,2] row_mask:0xf bank_mask:0xf
	v_mov_b32_dpp v103, v219 quad_perm:[1,0,3,2] row_mask:0xf bank_mask:0xf
	v_perm_b32 v216, v100, v216, v210
	v_perm_b32 v217, v101, v217, v210
	v_perm_b32 v218, v102, v218, v210
	v_perm_b32 v219, v103, v219, v210
	global_store_dword v[202:203], v216, off offset:32
	global_store_dword v[204:205], v217, off offset:32
	global_store_dword v[206:207], v218, off offset:32
	global_store_dword v[208:209], v219, off offset:32
	v_cvt_pk_bf16_f32 v212, v92, v93
	v_cvt_pk_bf16_f32 v213, v94, v95
	v_cvt_pk_bf16_f32 v214, v88, v89
	v_cvt_pk_bf16_f32 v215, v90, v91
	s_nop 0
	v_mov_b32_dpp v92, v212 quad_perm:[1,0,3,2] row_mask:0xf bank_mask:0xf
	v_mov_b32_dpp v93, v213 quad_perm:[1,0,3,2] row_mask:0xf bank_mask:0xf
	v_mov_b32_dpp v94, v214 quad_perm:[1,0,3,2] row_mask:0xf bank_mask:0xf
	v_mov_b32_dpp v95, v215 quad_perm:[1,0,3,2] row_mask:0xf bank_mask:0xf
	v_perm_b32 v212, v92, v212, v210
	v_perm_b32 v213, v93, v213, v210
	v_perm_b32 v214, v94, v214, v210
	v_perm_b32 v215, v95, v215, v210
	global_store_dword v[194:195], v212, off offset:64
	global_store_dword v[196:197], v213, off offset:64
	global_store_dword v[198:199], v214, off offset:64
	global_store_dword v[200:201], v215, off offset:64
	v_cvt_pk_bf16_f32 v216, v84, v85
	v_cvt_pk_bf16_f32 v217, v86, v87
	v_cvt_pk_bf16_f32 v218, v80, v81
	v_cvt_pk_bf16_f32 v219, v82, v83
	s_nop 0
	v_mov_b32_dpp v84, v216 quad_perm:[1,0,3,2] row_mask:0xf bank_mask:0xf
	v_mov_b32_dpp v85, v217 quad_perm:[1,0,3,2] row_mask:0xf bank_mask:0xf
	v_mov_b32_dpp v86, v218 quad_perm:[1,0,3,2] row_mask:0xf bank_mask:0xf
	v_mov_b32_dpp v87, v219 quad_perm:[1,0,3,2] row_mask:0xf bank_mask:0xf
	v_perm_b32 v216, v84, v216, v210
	v_perm_b32 v217, v85, v217, v210
	v_perm_b32 v218, v86, v218, v210
	v_perm_b32 v219, v87, v219, v210
	global_store_dword v[202:203], v216, off offset:64
	global_store_dword v[204:205], v217, off offset:64
	global_store_dword v[206:207], v218, off offset:64
	global_store_dword v[208:209], v219, off offset:64
	v_cvt_pk_bf16_f32 v212, v76, v77
	v_cvt_pk_bf16_f32 v213, v78, v79
	v_cvt_pk_bf16_f32 v214, v72, v73
	v_cvt_pk_bf16_f32 v215, v74, v75
	s_nop 0
	v_mov_b32_dpp v76, v212 quad_perm:[1,0,3,2] row_mask:0xf bank_mask:0xf
	v_mov_b32_dpp v77, v213 quad_perm:[1,0,3,2] row_mask:0xf bank_mask:0xf
	v_mov_b32_dpp v78, v214 quad_perm:[1,0,3,2] row_mask:0xf bank_mask:0xf
	v_mov_b32_dpp v79, v215 quad_perm:[1,0,3,2] row_mask:0xf bank_mask:0xf
	v_perm_b32 v212, v76, v212, v210
	v_perm_b32 v213, v77, v213, v210
	v_perm_b32 v214, v78, v214, v210
	v_perm_b32 v215, v79, v215, v210
	global_store_dword v[194:195], v212, off offset:96
	global_store_dword v[196:197], v213, off offset:96
	global_store_dword v[198:199], v214, off offset:96
	global_store_dword v[200:201], v215, off offset:96
	v_cvt_pk_bf16_f32 v216, v68, v69
	v_cvt_pk_bf16_f32 v217, v70, v71
	v_cvt_pk_bf16_f32 v218, v64, v65
	v_cvt_pk_bf16_f32 v219, v66, v67
	s_nop 0
	v_mov_b32_dpp v68, v216 quad_perm:[1,0,3,2] row_mask:0xf bank_mask:0xf
	v_mov_b32_dpp v69, v217 quad_perm:[1,0,3,2] row_mask:0xf bank_mask:0xf
	v_mov_b32_dpp v70, v218 quad_perm:[1,0,3,2] row_mask:0xf bank_mask:0xf
	v_mov_b32_dpp v71, v219 quad_perm:[1,0,3,2] row_mask:0xf bank_mask:0xf
	v_perm_b32 v216, v68, v216, v210
	v_perm_b32 v217, v69, v217, v210
	v_perm_b32 v218, v70, v218, v210
	v_perm_b32 v219, v71, v219, v210
	global_store_dword v[202:203], v216, off offset:96
	global_store_dword v[204:205], v217, off offset:96
	global_store_dword v[206:207], v218, off offset:96
	global_store_dword v[208:209], v219, off offset:96
	v_cvt_pk_bf16_f32 v212, v60, v61
	v_cvt_pk_bf16_f32 v213, v62, v63
	v_cvt_pk_bf16_f32 v214, v56, v57
	v_cvt_pk_bf16_f32 v215, v58, v59
	s_nop 0
	v_mov_b32_dpp v60, v212 quad_perm:[1,0,3,2] row_mask:0xf bank_mask:0xf
	v_mov_b32_dpp v61, v213 quad_perm:[1,0,3,2] row_mask:0xf bank_mask:0xf
	v_mov_b32_dpp v62, v214 quad_perm:[1,0,3,2] row_mask:0xf bank_mask:0xf
	v_mov_b32_dpp v63, v215 quad_perm:[1,0,3,2] row_mask:0xf bank_mask:0xf
	v_perm_b32 v212, v60, v212, v210
	v_perm_b32 v213, v61, v213, v210
	v_perm_b32 v214, v62, v214, v210
	v_perm_b32 v215, v63, v215, v210
	global_store_dword v[194:195], v212, off offset:256
	global_store_dword v[196:197], v213, off offset:256
	global_store_dword v[198:199], v214, off offset:256
	global_store_dword v[200:201], v215, off offset:256
	v_cvt_pk_bf16_f32 v216, v52, v53
	v_cvt_pk_bf16_f32 v217, v54, v55
	v_cvt_pk_bf16_f32 v218, v48, v49
	v_cvt_pk_bf16_f32 v219, v50, v51
	s_nop 0
	v_mov_b32_dpp v52, v216 quad_perm:[1,0,3,2] row_mask:0xf bank_mask:0xf
	v_mov_b32_dpp v53, v217 quad_perm:[1,0,3,2] row_mask:0xf bank_mask:0xf
	v_mov_b32_dpp v54, v218 quad_perm:[1,0,3,2] row_mask:0xf bank_mask:0xf
	v_mov_b32_dpp v55, v219 quad_perm:[1,0,3,2] row_mask:0xf bank_mask:0xf
	v_perm_b32 v216, v52, v216, v210
	v_perm_b32 v217, v53, v217, v210
	v_perm_b32 v218, v54, v218, v210
	v_perm_b32 v219, v55, v219, v210
	global_store_dword v[202:203], v216, off offset:256
	global_store_dword v[204:205], v217, off offset:256
	global_store_dword v[206:207], v218, off offset:256
	global_store_dword v[208:209], v219, off offset:256
	v_cvt_pk_bf16_f32 v212, v44, v45
	v_cvt_pk_bf16_f32 v213, v46, v47
	v_cvt_pk_bf16_f32 v214, v40, v41
	v_cvt_pk_bf16_f32 v215, v42, v43
	s_nop 0
	v_mov_b32_dpp v44, v212 quad_perm:[1,0,3,2] row_mask:0xf bank_mask:0xf
	v_mov_b32_dpp v45, v213 quad_perm:[1,0,3,2] row_mask:0xf bank_mask:0xf
	v_mov_b32_dpp v46, v214 quad_perm:[1,0,3,2] row_mask:0xf bank_mask:0xf
	v_mov_b32_dpp v47, v215 quad_perm:[1,0,3,2] row_mask:0xf bank_mask:0xf
	v_perm_b32 v212, v44, v212, v210
	v_perm_b32 v213, v45, v213, v210
	v_perm_b32 v214, v46, v214, v210
	v_perm_b32 v215, v47, v215, v210
	global_store_dword v[194:195], v212, off offset:288
	global_store_dword v[196:197], v213, off offset:288
	global_store_dword v[198:199], v214, off offset:288
	global_store_dword v[200:201], v215, off offset:288
	v_cvt_pk_bf16_f32 v216, v36, v37
	v_cvt_pk_bf16_f32 v217, v38, v39
	v_cvt_pk_bf16_f32 v218, v32, v33
	v_cvt_pk_bf16_f32 v219, v34, v35
	s_nop 0
	v_mov_b32_dpp v36, v216 quad_perm:[1,0,3,2] row_mask:0xf bank_mask:0xf
	v_mov_b32_dpp v37, v217 quad_perm:[1,0,3,2] row_mask:0xf bank_mask:0xf
	v_mov_b32_dpp v38, v218 quad_perm:[1,0,3,2] row_mask:0xf bank_mask:0xf
	v_mov_b32_dpp v39, v219 quad_perm:[1,0,3,2] row_mask:0xf bank_mask:0xf
	v_perm_b32 v216, v36, v216, v210
	v_perm_b32 v217, v37, v217, v210
	v_perm_b32 v218, v38, v218, v210
	v_perm_b32 v219, v39, v219, v210
	global_store_dword v[202:203], v216, off offset:288
	global_store_dword v[204:205], v217, off offset:288
	global_store_dword v[206:207], v218, off offset:288
	global_store_dword v[208:209], v219, off offset:288
	v_cvt_pk_bf16_f32 v212, v28, v29
	v_cvt_pk_bf16_f32 v213, v30, v31
	v_cvt_pk_bf16_f32 v214, v24, v25
	v_cvt_pk_bf16_f32 v215, v26, v27
	s_nop 0
	v_mov_b32_dpp v28, v212 quad_perm:[1,0,3,2] row_mask:0xf bank_mask:0xf
	v_mov_b32_dpp v29, v213 quad_perm:[1,0,3,2] row_mask:0xf bank_mask:0xf
	v_mov_b32_dpp v30, v214 quad_perm:[1,0,3,2] row_mask:0xf bank_mask:0xf
	v_mov_b32_dpp v31, v215 quad_perm:[1,0,3,2] row_mask:0xf bank_mask:0xf
	v_perm_b32 v212, v28, v212, v210
	v_perm_b32 v213, v29, v213, v210
	v_perm_b32 v214, v30, v214, v210
	v_perm_b32 v215, v31, v215, v210
	global_store_dword v[194:195], v212, off offset:320
	global_store_dword v[196:197], v213, off offset:320
	global_store_dword v[198:199], v214, off offset:320
	global_store_dword v[200:201], v215, off offset:320
	v_cvt_pk_bf16_f32 v216, v20, v21
	v_cvt_pk_bf16_f32 v217, v22, v23
	v_cvt_pk_bf16_f32 v218, v16, v17
	v_cvt_pk_bf16_f32 v219, v18, v19
	s_nop 0
	v_mov_b32_dpp v20, v216 quad_perm:[1,0,3,2] row_mask:0xf bank_mask:0xf
	v_mov_b32_dpp v21, v217 quad_perm:[1,0,3,2] row_mask:0xf bank_mask:0xf
	v_mov_b32_dpp v22, v218 quad_perm:[1,0,3,2] row_mask:0xf bank_mask:0xf
	v_mov_b32_dpp v23, v219 quad_perm:[1,0,3,2] row_mask:0xf bank_mask:0xf
	v_perm_b32 v216, v20, v216, v210
	v_perm_b32 v217, v21, v217, v210
	v_perm_b32 v218, v22, v218, v210
	v_perm_b32 v219, v23, v219, v210
	global_store_dword v[202:203], v216, off offset:320
	global_store_dword v[204:205], v217, off offset:320
	global_store_dword v[206:207], v218, off offset:320
	global_store_dword v[208:209], v219, off offset:320
	v_cvt_pk_bf16_f32 v212, v12, v13
	v_cvt_pk_bf16_f32 v213, v14, v15
	v_cvt_pk_bf16_f32 v214, v8, v9
	v_cvt_pk_bf16_f32 v215, v10, v11
	s_nop 0
	v_mov_b32_dpp v12, v212 quad_perm:[1,0,3,2] row_mask:0xf bank_mask:0xf
	v_mov_b32_dpp v13, v213 quad_perm:[1,0,3,2] row_mask:0xf bank_mask:0xf
	v_mov_b32_dpp v14, v214 quad_perm:[1,0,3,2] row_mask:0xf bank_mask:0xf
	v_mov_b32_dpp v15, v215 quad_perm:[1,0,3,2] row_mask:0xf bank_mask:0xf
	v_perm_b32 v212, v12, v212, v210
	v_perm_b32 v213, v13, v213, v210
	v_perm_b32 v214, v14, v214, v210
	v_perm_b32 v215, v15, v215, v210
	global_store_dword v[194:195], v212, off offset:352
	global_store_dword v[196:197], v213, off offset:352
	global_store_dword v[198:199], v214, off offset:352
	global_store_dword v[200:201], v215, off offset:352
	v_cvt_pk_bf16_f32 v216, v4, v5
	v_cvt_pk_bf16_f32 v217, v6, v7
	v_cvt_pk_bf16_f32 v218, v0, v1
	v_cvt_pk_bf16_f32 v219, v2, v3
	s_nop 0
	v_mov_b32_dpp v4, v216 quad_perm:[1,0,3,2] row_mask:0xf bank_mask:0xf
	v_mov_b32_dpp v5, v217 quad_perm:[1,0,3,2] row_mask:0xf bank_mask:0xf
	v_mov_b32_dpp v6, v218 quad_perm:[1,0,3,2] row_mask:0xf bank_mask:0xf
	v_mov_b32_dpp v7, v219 quad_perm:[1,0,3,2] row_mask:0xf bank_mask:0xf
	v_perm_b32 v216, v4, v216, v210
	v_perm_b32 v217, v5, v217, v210
	v_perm_b32 v218, v6, v218, v210
	v_perm_b32 v219, v7, v219, v210
	global_store_dword v[202:203], v216, off offset:352
	global_store_dword v[204:205], v217, off offset:352
	global_store_dword v[206:207], v218, off offset:352
	global_store_dword v[208:209], v219, off offset:352
	s_branch .LBB0_1065
